# barrier: invalidate issued right after the arrival atomic, arrival no longer waits for it
# speedup vs baseline: 1.0604x; 1.0058x over previous
.LBB0_65:
	s_cbranch_execz .LBB0_119
	s_waitcnt vmcnt(0)
	s_barrier
	s_mov_b64 s[8:9], exec
	v_readlane_b32 s6, v255, 4
	v_readlane_b32 s7, v255, 5
	s_and_b64 s[6:7], s[8:9], s[6:7]
	s_mov_b64 exec, s[6:7]
	s_cbranch_execz .LBB0_118
	s_add_i32 s3, 0, 0x22020
	v_mov_b32_e32 v1, s3
	s_waitcnt lgkmcnt(0)
	ds_read_b32 v4, v1
	s_add_i32 s3, 0, 0x22024
	v_mov_b32_e32 v1, s3
	ds_read_b32 v2, v1
	s_waitcnt lgkmcnt(1)
	v_cmp_ne_u32_e32 vcc, 0, v4
	s_cbranch_vccnz .LBB0_82
	v_readlane_b32 s10, v255, 1
	v_readlane_b32 s11, v255, 2
	s_load_dwordx2 s[6:7], s[10:11], 0x4
	s_add_u32 s10, s88, 0x1200
	s_addc_u32 s11, s89, 0
	s_add_u32 s12, s88, 0x1400
	s_addc_u32 s13, s89, 0
	s_add_u32 s14, s88, 0x1500
	s_addc_u32 s15, s89, 0
	s_add_u32 s16, s88, 0x1600
	s_addc_u32 s17, s89, 0
	s_add_u32 s18, s88, 0x1700
	s_addc_u32 s19, s89, 0
	s_add_u32 s20, s88, 0x1800
	s_addc_u32 s21, s89, 0
	s_add_u32 s22, s88, 0x1900
	s_addc_u32 s23, s89, 0
	s_add_u32 s24, s88, 0x1a00
	s_addc_u32 s25, s89, 0
	s_add_u32 s26, s88, 0x1b00
	s_addc_u32 s27, s89, 0
	s_add_u32 s28, s88, 0x1c00
	s_addc_u32 s29, s89, 0
	s_add_u32 s30, s88, 0x1d00
	s_addc_u32 s31, s89, 0
	s_add_u32 s34, s88, 0x1e00
	s_addc_u32 s35, s89, 0
	s_add_u32 s36, s88, 0x1f00
	s_addc_u32 s37, s89, 0
	s_add_u32 s38, s88, 0x2000
	s_addc_u32 s39, s89, 0
	s_add_u32 s40, s88, 0x2100
	s_addc_u32 s41, s89, 0
	s_add_u32 s42, s88, 0x2200
	s_addc_u32 s43, s89, 0
	s_waitcnt lgkmcnt(0)
	s_mul_i32 s3, s6, s33
	s_add_u32 s44, s88, 0x2300
	s_mul_i32 s3, s3, s7
	s_addc_u32 s45, s89, 0
	s_mov_b32 s6, 1
	v_mov_b32_e32 v18, 0
	s_branch .LBB0_70

.LBB0_84:
	s_or_b64 exec, exec, s[14:15]
	buffer_inv sc1
	v_cvt_f32_u32_e32 v1, v4
	s_waitcnt vmcnt(1)
	v_readfirstlane_b32 s3, v5
	v_sub_u32_e32 v5, 0, v4
	v_rcp_iflag_f32_e32 v1, v1
	v_add_u32_e32 v6, s3, v3
	v_mul_f32_e32 v1, 0x4f7ffffe, v1
	v_cvt_u32_f32_e32 v1, v1
	v_mul_lo_u32 v3, v5, v1
	v_mul_hi_u32 v3, v1, v3
	v_add_u32_e32 v1, v1, v3
	v_mul_hi_u32 v1, v6, v1
	v_mul_lo_u32 v3, v1, v4
	v_sub_u32_e32 v3, v6, v3
	v_add_u32_e32 v5, 1, v1
	v_cmp_ge_u32_e32 vcc, v3, v4
	s_nop 1
	v_cndmask_b32_e32 v1, v1, v5, vcc
	v_sub_u32_e32 v5, v3, v4
	v_cndmask_b32_e32 v3, v3, v5, vcc
	v_add_u32_e32 v5, 1, v1
	v_cmp_ge_u32_e32 vcc, v3, v4
	s_nop 1
	v_cndmask_b32_e32 v3, v1, v5, vcc
	v_mul_lo_u32 v5, v4, v3
	v_add_u32_e32 v1, 1, v6
	v_add_u32_e32 v4, v5, v4
	v_cmp_ne_u32_e32 vcc, v1, v4
	s_and_saveexec_b64 s[6:7], vcc
	s_xor_b64 s[12:13], exec, s[6:7]
	s_cbranch_execz .LBB0_98
	v_mov_b32_e32 v1, 0
	s_add_u32 s18, s88, 0x4500
	s_addc_u32 s19, s89, 0
	global_load_dword v1, v1, s[18:19] sc1
	s_waitcnt vmcnt(0)
	v_cmp_eq_u32_e32 vcc, v1, v3
	s_and_saveexec_b64 s[14:15], vcc
	s_cbranch_execz .LBB0_97
	s_add_u32 s16, s88, 0x1200
	s_addc_u32 s17, s89, 0
	s_mov_b32 s3, 1
	s_mov_b64 s[20:21], 0
	s_waitcnt lgkmcnt(0)
	v_mov_b32_e32 v2, 0
	s_branch .LBB0_88

.LBB0_147:
	s_cbranch_execz .LBB0_201
	s_waitcnt vmcnt(0)
	s_waitcnt lgkmcnt(0)
	s_barrier
	s_mov_b64 s[4:5], exec
	v_readlane_b32 s6, v255, 4
	v_readlane_b32 s7, v255, 5
	s_and_b64 s[6:7], s[4:5], s[6:7]
	s_mov_b64 exec, s[6:7]
	s_cbranch_execz .LBB0_200
	s_add_i32 s3, 0, 0x22020
	v_mov_b32_e32 v1, s3
	s_waitcnt lgkmcnt(0)
	ds_read_b32 v4, v1
	s_add_i32 s3, 0, 0x22024
	v_mov_b32_e32 v1, s3
	ds_read_b32 v2, v1
	s_waitcnt lgkmcnt(1)
	v_cmp_ne_u32_e32 vcc, 0, v4
	s_cbranch_vccnz .LBB0_164
	v_readlane_b32 s8, v255, 1
	v_readlane_b32 s9, v255, 2
	s_load_dwordx2 s[6:7], s[8:9], 0x4
	s_add_u32 s8, s88, 0x1200
	s_addc_u32 s9, s89, 0
	s_add_u32 s10, s88, 0x1400
	s_addc_u32 s11, s89, 0
	s_add_u32 s12, s88, 0x1500
	s_addc_u32 s13, s89, 0
	s_add_u32 s14, s88, 0x1600
	s_addc_u32 s15, s89, 0
	s_add_u32 s16, s88, 0x1700
	s_addc_u32 s17, s89, 0
	s_add_u32 s18, s88, 0x1800
	s_addc_u32 s19, s89, 0
	s_add_u32 s20, s88, 0x1900
	s_addc_u32 s21, s89, 0
	s_add_u32 s22, s88, 0x1a00
	s_addc_u32 s23, s89, 0
	s_add_u32 s24, s88, 0x1b00
	s_addc_u32 s25, s89, 0
	s_add_u32 s26, s88, 0x1c00
	s_addc_u32 s27, s89, 0
	s_add_u32 s28, s88, 0x1d00
	s_addc_u32 s29, s89, 0
	s_add_u32 s30, s88, 0x1e00
	s_addc_u32 s31, s89, 0
	s_add_u32 s34, s88, 0x1f00
	s_addc_u32 s35, s89, 0
	s_add_u32 s36, s88, 0x2000
	s_addc_u32 s37, s89, 0
	s_add_u32 s38, s88, 0x2100
	s_addc_u32 s39, s89, 0
	s_add_u32 s40, s88, 0x2200
	s_addc_u32 s41, s89, 0
	s_waitcnt lgkmcnt(0)
	s_mul_i32 s3, s6, s33
	s_add_u32 s42, s88, 0x2300
	s_mul_i32 s3, s3, s7
	s_addc_u32 s43, s89, 0
	s_mov_b32 s6, 1
	v_mov_b32_e32 v18, 0
	s_branch .LBB0_152

.LBB0_166:
	s_or_b64 exec, exec, s[12:13]
	buffer_inv sc1
	v_cvt_f32_u32_e32 v1, v4
	s_waitcnt vmcnt(1)
	v_readfirstlane_b32 s3, v5
	v_sub_u32_e32 v5, 0, v4
	v_rcp_iflag_f32_e32 v1, v1
	v_add_u32_e32 v6, s3, v3
	v_mul_f32_e32 v1, 0x4f7ffffe, v1
	v_cvt_u32_f32_e32 v1, v1
	v_mul_lo_u32 v3, v5, v1
	v_mul_hi_u32 v3, v1, v3
	v_add_u32_e32 v1, v1, v3
	v_mul_hi_u32 v1, v6, v1
	v_mul_lo_u32 v3, v1, v4
	v_sub_u32_e32 v3, v6, v3
	v_add_u32_e32 v5, 1, v1
	v_cmp_ge_u32_e32 vcc, v3, v4
	s_nop 1
	v_cndmask_b32_e32 v1, v1, v5, vcc
	v_sub_u32_e32 v5, v3, v4
	v_cndmask_b32_e32 v3, v3, v5, vcc
	v_add_u32_e32 v5, 1, v1
	v_cmp_ge_u32_e32 vcc, v3, v4
	s_nop 1
	v_cndmask_b32_e32 v3, v1, v5, vcc
	v_mul_lo_u32 v5, v4, v3
	v_add_u32_e32 v1, 1, v6
	v_add_u32_e32 v4, v5, v4
	v_cmp_ne_u32_e32 vcc, v1, v4
	s_and_saveexec_b64 s[6:7], vcc
	s_xor_b64 s[10:11], exec, s[6:7]
	s_cbranch_execz .LBB0_180
	v_mov_b32_e32 v1, 0
	s_add_u32 s16, s88, 0x4500
	s_addc_u32 s17, s89, 0
	global_load_dword v1, v1, s[16:17] sc1
	s_waitcnt vmcnt(0)
	v_cmp_eq_u32_e32 vcc, v1, v3
	s_and_saveexec_b64 s[12:13], vcc
	s_cbranch_execz .LBB0_179
	s_add_u32 s14, s88, 0x1200
	s_addc_u32 s15, s89, 0
	s_mov_b32 s3, 1
	s_mov_b64 s[18:19], 0
	s_waitcnt lgkmcnt(0)
	v_mov_b32_e32 v2, 0
	s_branch .LBB0_170

.LBB0_486:
	s_cbranch_execz .LBB0_540
	s_waitcnt vmcnt(0)
	s_waitcnt lgkmcnt(0)
	s_barrier
	s_mov_b64 s[4:5], exec
	v_readlane_b32 s6, v255, 4
	v_readlane_b32 s7, v255, 5
	s_and_b64 s[6:7], s[4:5], s[6:7]
	s_mov_b64 exec, s[6:7]
	s_cbranch_execz .LBB0_539
	s_add_i32 s3, 0, 0x22020
	v_mov_b32_e32 v1, s3
	s_waitcnt lgkmcnt(0)
	ds_read_b32 v4, v1
	s_add_i32 s3, 0, 0x22024
	v_mov_b32_e32 v1, s3
	ds_read_b32 v2, v1
	s_waitcnt lgkmcnt(1)
	v_cmp_ne_u32_e32 vcc, 0, v4
	s_cbranch_vccnz .LBB0_503
	v_readlane_b32 s8, v255, 1
	v_readlane_b32 s9, v255, 2
	s_load_dwordx2 s[6:7], s[8:9], 0x4
	s_add_u32 s8, s88, 0x1200
	s_addc_u32 s9, s89, 0
	s_add_u32 s12, s88, 0x1400
	s_addc_u32 s13, s89, 0
	s_add_u32 s14, s88, 0x1500
	s_addc_u32 s15, s89, 0
	s_add_u32 s16, s88, 0x1600
	s_addc_u32 s17, s89, 0
	s_add_u32 s18, s88, 0x1700
	s_addc_u32 s19, s89, 0
	s_add_u32 s20, s88, 0x1800
	s_addc_u32 s21, s89, 0
	s_add_u32 s22, s88, 0x1900
	s_addc_u32 s23, s89, 0
	s_add_u32 s24, s88, 0x1a00
	s_addc_u32 s25, s89, 0
	s_add_u32 s26, s88, 0x1b00
	s_addc_u32 s27, s89, 0
	s_add_u32 s28, s88, 0x1c00
	s_addc_u32 s29, s89, 0
	s_add_u32 s30, s88, 0x1d00
	s_addc_u32 s31, s89, 0
	s_add_u32 s34, s88, 0x1e00
	s_addc_u32 s35, s89, 0
	s_add_u32 s36, s88, 0x1f00
	s_addc_u32 s37, s89, 0
	s_add_u32 s38, s88, 0x2000
	s_addc_u32 s39, s89, 0
	s_add_u32 s40, s88, 0x2100
	s_addc_u32 s41, s89, 0
	s_add_u32 s42, s88, 0x2200
	s_addc_u32 s43, s89, 0
	s_waitcnt lgkmcnt(0)
	s_mul_i32 s3, s6, s33
	s_add_u32 s44, s88, 0x2300
	s_mul_i32 s3, s3, s7
	s_addc_u32 s45, s89, 0
	s_mov_b32 s6, 1
	v_mov_b32_e32 v18, 0
	s_branch .LBB0_491

.LBB0_1366:
	s_cbranch_execz .LBB0_1420
	s_waitcnt vmcnt(0)
	s_waitcnt vmcnt(0) lgkmcnt(0)
	s_barrier
	s_mov_b64 s[4:5], exec
	v_readlane_b32 s6, v255, 4
	v_readlane_b32 s7, v255, 5
	s_and_b64 s[6:7], s[4:5], s[6:7]
	s_mov_b64 exec, s[6:7]
	s_cbranch_execz .LBB0_1419
	s_add_i32 s3, 0, 0x22020
	v_mov_b32_e32 v0, s3
	s_waitcnt lgkmcnt(0)
	ds_read_b32 v2, v0
	s_add_i32 s3, 0, 0x22024
	v_mov_b32_e32 v0, s3
	ds_read_b32 v0, v0
	s_waitcnt lgkmcnt(1)
	v_cmp_ne_u32_e32 vcc, 0, v2
	s_cbranch_vccnz .LBB0_1383
	v_readlane_b32 s6, v255, 1
	v_readlane_b32 s7, v255, 2
	s_load_dwordx2 s[12:13], s[6:7], 0x4
	s_add_u32 s6, s88, 0x1200
	s_addc_u32 s7, s89, 0
	s_add_u32 s8, s88, 0x1400
	s_addc_u32 s9, s89, 0
	s_waitcnt lgkmcnt(0)
	s_mul_i32 s3, s12, s33
	s_add_u32 s12, s88, 0x1500
	s_mul_i32 s3, s3, s13
	s_addc_u32 s13, s89, 0
	s_add_u32 s14, s88, 0x1600
	s_addc_u32 s15, s89, 0
	s_add_u32 s16, s88, 0x1700
	s_addc_u32 s17, s89, 0
	s_add_u32 s18, s88, 0x1800
	s_addc_u32 s19, s89, 0
	s_add_u32 s20, s88, 0x1900
	s_addc_u32 s21, s89, 0
	s_add_u32 s22, s88, 0x1a00
	s_addc_u32 s23, s89, 0
	s_add_u32 s24, s88, 0x1b00
	s_addc_u32 s25, s89, 0
	s_add_u32 s26, s88, 0x1c00
	s_addc_u32 s27, s89, 0
	s_add_u32 s28, s88, 0x1d00
	s_addc_u32 s29, s89, 0
	s_add_u32 s30, s88, 0x1e00
	s_addc_u32 s31, s89, 0
	s_add_u32 s34, s88, 0x1f00
	s_addc_u32 s35, s89, 0
	s_add_u32 s36, s88, 0x2000
	s_addc_u32 s37, s89, 0
	s_add_u32 s38, s88, 0x2100
	s_addc_u32 s39, s89, 0
	s_add_u32 s40, s88, 0x2200
	s_addc_u32 s41, s89, 0
	s_add_u32 s42, s88, 0x2300
	s_addc_u32 s43, s89, 0
	s_mov_b32 s50, 1
	v_mov_b32_e32 v16, 0
	s_branch .LBB0_1371

.LBB0_1385:
	s_or_b64 exec, exec, s[12:13]
	buffer_inv sc1
	v_cvt_f32_u32_e32 v4, v2
	s_waitcnt vmcnt(1)
	v_readfirstlane_b32 s3, v3
	v_sub_u32_e32 v3, 0, v2
	v_rcp_iflag_f32_e32 v4, v4
	v_add_u32_e32 v5, s3, v1
	v_mul_f32_e32 v4, 0x4f7ffffe, v4
	v_cvt_u32_f32_e32 v4, v4
	v_mul_lo_u32 v1, v3, v4
	v_mul_hi_u32 v1, v4, v1
	v_add_u32_e32 v1, v4, v1
	v_mul_hi_u32 v1, v5, v1
	v_mul_lo_u32 v3, v1, v2
	v_sub_u32_e32 v3, v5, v3
	v_add_u32_e32 v4, 1, v1
	v_cmp_ge_u32_e32 vcc, v3, v2
	s_nop 1
	v_cndmask_b32_e32 v1, v1, v4, vcc
	v_sub_u32_e32 v4, v3, v2
	v_cndmask_b32_e32 v3, v3, v4, vcc
	v_add_u32_e32 v4, 1, v1
	v_cmp_ge_u32_e32 vcc, v3, v2
	v_add_u32_e32 v3, 1, v5
	s_nop 0
	v_cndmask_b32_e32 v1, v1, v4, vcc
	v_mul_lo_u32 v4, v2, v1
	v_add_u32_e32 v2, v4, v2
	v_cmp_ne_u32_e32 vcc, v3, v2
	s_and_saveexec_b64 s[8:9], vcc
	s_xor_b64 s[8:9], exec, s[8:9]
	s_cbranch_execz .LBB0_1399
	s_waitcnt lgkmcnt(0)
	v_mov_b32_e32 v0, 0
	s_add_u32 s16, s88, 0x4500
	s_addc_u32 s17, s89, 0
	global_load_dword v0, v0, s[16:17] sc1
	s_waitcnt vmcnt(0)
	v_cmp_eq_u32_e32 vcc, v0, v1
	s_and_saveexec_b64 s[12:13], vcc
	s_cbranch_execz .LBB0_1398
	s_add_u32 s14, s88, 0x1200
	s_addc_u32 s15, s89, 0
	s_mov_b32 s3, 1
	s_mov_b64 s[18:19], 0
	v_mov_b32_e32 v0, 0
	s_branch .LBB0_1389
